# MLA loop head: wave-uniform steady-state test done on the scalar unit (nw in m0) instead of v_cmp + exec masking, loop-edge shortening
# baseline (speedup 1.0000x reference)
.LBB0_436:
	s_or_b64 exec, exec, s[78:79]
	v_or_b32_e32 v16, 2, v171
	v_ashrrev_i32_e32 v21, 7, v18
	v_lshrrev_b32_e32 v18, 1, v18
	v_or_b32_e32 v17, 4, v171
	v_bitop3_b32 v16, v16, v18, 7 bitop3:0x78
	v_or_b32_e32 v20, 6, v171
	v_lshlrev_b32_e32 v200, 4, v16
	v_bitop3_b32 v16, v17, v18, 7 bitop3:0x78
	s_lshl_b32 s70, s18, 2
	v_lshlrev_b32_e32 v198, 7, v19
	v_bitop3_b32 v19, v171, v18, 7 bitop3:0x78
	v_lshlrev_b32_e32 v201, 4, v16
	v_bitop3_b32 v16, v20, v18, 7 bitop3:0x78
	v_add3_u32 v197, v21, s70, 1
	v_lshlrev_b32_e32 v199, 4, v19
	v_lshlrev_b32_e32 v202, 4, v16
	v_mov_b64_e32 v[30:31], v[14:15]
	v_mov_b64_e32 v[46:47], v[14:15]
	s_lshl_b32 s5, s19, 6
	s_add_i32 s70, s70, 4
	s_mov_b32 s73, 0
	v_mov_b32_e32 v203, 0
	s_movk_i32 s14, 0xc0
	s_movk_i32 s71, 0x2000
	s_movk_i32 s72, 0x4000
	v_mov_b32_e32 v153, 0
	v_mov_b32_e32 v154, 0
	v_mov_b32_e32 v155, 0
	v_mov_b64_e32 v[28:29], v[12:13]
	v_mov_b64_e32 v[26:27], v[10:11]
	v_mov_b64_e32 v[24:25], v[8:9]
	v_mov_b64_e32 v[22:23], v[6:7]
	v_mov_b64_e32 v[20:21], v[4:5]
	v_mov_b64_e32 v[18:19], v[2:3]
	v_mov_b64_e32 v[16:17], v[0:1]
	v_mov_b64_e32 v[44:45], v[12:13]
	v_mov_b64_e32 v[42:43], v[10:11]
	v_mov_b64_e32 v[40:41], v[8:9]
	v_mov_b64_e32 v[38:39], v[6:7]
	v_mov_b64_e32 v[36:37], v[4:5]
	v_mov_b64_e32 v[34:35], v[2:3]
	v_mov_b64_e32 v[32:33], v[0:1]
	v_or_b32_e32 v186, v186, v194
	v_or_b32_e32 v184, v184, v194
	v_or_b32_e32 v183, v183, v194
	v_or_b32_e32 v191, v191, v194
	v_or_b32_e32 v190, v190, v194
	v_or_b32_e32 v187, v187, v194
	v_add_u32_e32 v199, v198, v199
	v_add_u32_e32 v200, v198, v200
	v_add_u32_e32 v201, v198, v201
	v_add_u32_e32 v202, v198, v202
	v_readfirstlane_b32 s99, v197
	s_nop 3
	s_mov_b32 m0, s99
.LBB0_437:
	s_mov_b32 s98, 0
	s_and_b32 s68, s73, 1
	s_add_i32 s74, s73, 1
	s_lshl_b32 s69, s68, 13
	s_cmp_lt_i32 s74, m0
	s_cbranch_scc1 .Lmla_fast_e
	v_cmp_ge_i32_e32 vcc, s74, v197
	s_and_saveexec_b64 s[18:19], vcc
	s_xor_b64 s[86:87], exec, s[18:19]
	s_cbranch_execz .LBB0_445
	v_cmp_lt_i32_e32 vcc, s73, v197
	s_and_saveexec_b64 s[78:79], vcc
	s_cbranch_execz .LBB0_444
	v_max_f32_e32 v80, v65, v65
	v_max_f32_e32 v81, v64, v64
	v_max_f32_e32 v80, v81, v80
	v_max3_f32 v80, v80, v66, v67
	v_max3_f32 v80, v80, v68, v69
	v_max3_f32 v80, v80, v70, v71
	v_max3_f32 v80, v80, v72, v73
	v_max3_f32 v80, v80, v74, v75
	v_max3_f32 v80, v80, v76, v77
	v_max3_f32 v80, v80, v78, v79
	v_max3_f32 v80, v80, v48, v49
	v_max3_f32 v80, v80, v50, v51
	v_max3_f32 v80, v80, v52, v53
	v_max3_f32 v80, v80, v54, v55
	v_max3_f32 v80, v80, v56, v57
	v_max3_f32 v80, v80, v58, v59
	v_max3_f32 v80, v80, v60, v61
	s_cmp_eq_u32 s73, 0
	v_max3_f32 v80, v80, v62, v63
	s_cselect_b64 s[18:19], -1, 0
	v_cmp_lt_f32_e32 vcc, s29, v80
	s_or_b64 vcc, s[18:19], vcc
	s_cbranch_vccz .LBB0_443
	v_and_b32_e32 v82, 64, v172
	v_xor_b32_e32 v81, 32, v172
	v_add_u32_e32 v82, 64, v82
	v_cmp_lt_i32_e32 vcc, v81, v82
	v_mov_b32_e32 v155, 0
	s_nop 0
	v_cndmask_b32_e32 v81, v172, v81, vcc
	v_lshlrev_b32_e32 v81, 2, v81
	ds_bpermute_b32 v81, v81, v80
	v_max_f32_e32 v80, v80, v80
	s_waitcnt lgkmcnt(0)
	v_max_f32_e32 v81, v81, v81
	v_max_f32_e32 v81, v80, v81
	v_cmp_lt_f32_e32 vcc, s30, v81
	s_and_b64 s[18:19], s[18:19], vcc
	v_cmp_lt_f32_e32 vcc, s29, v81
	s_or_b64 vcc, vcc, s[18:19]
	v_mov_b32_e32 v80, 0
	s_and_saveexec_b64 s[18:19], vcc
	v_add_f32_e32 v80, v203, v81
	v_cvt_pk_bf16_f32 v80, v80, 0
	v_lshlrev_b32_e32 v81, 16, v80
	v_sub_f32_e32 v80, v81, v203
	v_mov_b32_e32 v203, v81
	s_or_b64 exec, exec, s[18:19]
	v_exp_f32_e64 v82, -v80
	s_mov_b64 vcc, s[8:9]
	v_sub_f32_e32 v79, v79, v80
	v_sub_f32_e32 v78, v78, v80
	v_sub_f32_e32 v77, v77, v80
	v_sub_f32_e32 v76, v76, v80
	v_sub_f32_e32 v75, v75, v80
	v_sub_f32_e32 v74, v74, v80
	v_sub_f32_e32 v73, v73, v80
	v_sub_f32_e32 v72, v72, v80
	v_sub_f32_e32 v71, v71, v80
	v_sub_f32_e32 v70, v70, v80
	v_sub_f32_e32 v69, v69, v80
	v_sub_f32_e32 v68, v68, v80
	v_sub_f32_e32 v67, v67, v80
	v_sub_f32_e32 v66, v66, v80
	v_sub_f32_e32 v65, v65, v80
	v_sub_f32_e32 v64, v64, v80
	v_sub_f32_e32 v63, v63, v80
	v_sub_f32_e32 v62, v62, v80
	v_sub_f32_e32 v61, v61, v80
	v_sub_f32_e32 v60, v60, v80
	v_sub_f32_e32 v59, v59, v80
	v_sub_f32_e32 v58, v58, v80
	v_sub_f32_e32 v57, v57, v80
	v_sub_f32_e32 v56, v56, v80
	v_sub_f32_e32 v55, v55, v80
	v_sub_f32_e32 v54, v54, v80
	v_sub_f32_e32 v53, v53, v80
	v_sub_f32_e32 v52, v52, v80
	v_sub_f32_e32 v51, v51, v80
	v_sub_f32_e32 v50, v50, v80
	v_sub_f32_e32 v49, v49, v80
	v_sub_f32_e32 v48, v48, v80
	v_xor_b32_e32 v80, 0x80000000, v203
	v_pk_mul_f32 v[46:47], v[46:47], v[82:83] op_sel_hi:[1,0]
	v_pk_mul_f32 v[44:45], v[44:45], v[82:83] op_sel_hi:[1,0]
	v_pk_mul_f32 v[42:43], v[42:43], v[82:83] op_sel_hi:[1,0]
	v_pk_mul_f32 v[40:41], v[40:41], v[82:83] op_sel_hi:[1,0]
	v_pk_mul_f32 v[38:39], v[38:39], v[82:83] op_sel_hi:[1,0]
	v_pk_mul_f32 v[36:37], v[36:37], v[82:83] op_sel_hi:[1,0]
	v_pk_mul_f32 v[34:35], v[34:35], v[82:83] op_sel_hi:[1,0]
	v_pk_mul_f32 v[32:33], v[32:33], v[82:83] op_sel_hi:[1,0]
	v_pk_mul_f32 v[30:31], v[30:31], v[82:83] op_sel_hi:[1,0]
	v_pk_mul_f32 v[28:29], v[28:29], v[82:83] op_sel_hi:[1,0]
	v_pk_mul_f32 v[26:27], v[26:27], v[82:83] op_sel_hi:[1,0]
	v_pk_mul_f32 v[24:25], v[24:25], v[82:83] op_sel_hi:[1,0]
	v_pk_mul_f32 v[22:23], v[22:23], v[82:83] op_sel_hi:[1,0]
	v_pk_mul_f32 v[20:21], v[20:21], v[82:83] op_sel_hi:[1,0]
	v_pk_mul_f32 v[18:19], v[18:19], v[82:83] op_sel_hi:[1,0]
	v_pk_mul_f32 v[16:17], v[16:17], v[82:83] op_sel_hi:[1,0]
	v_pk_mul_f32 v[14:15], v[14:15], v[82:83] op_sel_hi:[1,0]
	v_pk_mul_f32 v[12:13], v[12:13], v[82:83] op_sel_hi:[1,0]
	v_pk_mul_f32 v[10:11], v[10:11], v[82:83] op_sel_hi:[1,0]
	v_pk_mul_f32 v[8:9], v[8:9], v[82:83] op_sel_hi:[1,0]
	v_pk_mul_f32 v[6:7], v[6:7], v[82:83] op_sel_hi:[1,0]
	v_pk_mul_f32 v[4:5], v[4:5], v[82:83] op_sel_hi:[1,0]
	v_pk_mul_f32 v[2:3], v[2:3], v[82:83] op_sel_hi:[1,0]
	v_pk_mul_f32 v[0:1], v[0:1], v[82:83] op_sel_hi:[1,0]
	v_cndmask_b32_sdwa v152, v113, v80, vcc dst_sel:DWORD dst_unused:UNUSED_PAD src0_sel:DWORD src1_sel:WORD_1
	v_mov_b32_e32 v154, 0
	v_mov_b32_e32 v153, 0

.Lmla_fast_e:
	ds_read_b128 v[174:177], v186 offset:16384
	ds_read_b128 v[204:207], v186 offset:24576
	v_mfma_f32_32x32x16_bf16 v[80:95], v[112:115], v[152:155], 0
	ds_read_b128 v[208:211], v184 offset:16384
	ds_read_b128 v[212:215], v184 offset:24576
	ds_read_b128 v[216:219], v183 offset:16384
	ds_read_b128 v[220:223], v183 offset:24576
	ds_read_b128 v[230:233], v191 offset:16384
	ds_read_b128 v[234:237], v191 offset:24576
	ds_read_b128 v[238:241], v190 offset:16384
	ds_read_b128 v[242:245], v190 offset:24576
	ds_read_b128 v[246:249], v187 offset:16384
	ds_read_b128 v[250:253], v187 offset:24576
	s_cmp_eq_u32 s73, 0
	s_cselect_b64 s[78:79], -1, 0
	v_max_f32_e32 v224, v65, v65
	v_max_f32_e32 v225, v64, v64
	v_max_f32_e32 v224, v225, v224
	v_max3_f32 v224, v224, v66, v67
	v_max3_f32 v224, v224, v68, v69
	s_waitcnt lgkmcnt(11)
	v_mfma_f32_32x32x16_bf16 v[96:111], v[174:177], v[116:119], v[80:95]
	v_max3_f32 v224, v224, v70, v71
	v_max3_f32 v224, v224, v72, v73
	v_max3_f32 v224, v224, v74, v75
	v_max3_f32 v224, v224, v76, v77
	v_max3_f32 v224, v224, v78, v79
	v_max3_f32 v224, v224, v48, v49
	s_waitcnt lgkmcnt(10)
	v_mfma_f32_32x32x16_bf16 v[80:95], v[204:207], v[116:119], v[80:95]
	ds_read_b128 v[174:177], v199 offset:32768
	v_max3_f32 v224, v224, v50, v51
	v_max3_f32 v224, v224, v52, v53
	v_max3_f32 v224, v224, v54, v55
	v_max3_f32 v224, v224, v56, v57
	v_max3_f32 v224, v224, v58, v59
	v_max3_f32 v224, v224, v60, v61
	v_max3_f32 v229, v224, v62, v63
	v_cmp_lt_f32_e32 vcc, s29, v229
	s_or_b64 vcc, s[78:79], vcc
	s_waitcnt lgkmcnt(10)
	v_mfma_f32_32x32x16_bf16 v[96:111], v[208:211], v[120:123], v[96:111]
	ds_read_b128 v[204:207], v199 offset:36864
	s_cbranch_vccz .LBB0_450
	v_and_b32_e32 v153, 64, v172
	v_xor_b32_e32 v152, 32, v172
	v_add_u32_e32 v153, 64, v153
	v_cmp_lt_i32_e32 vcc, v152, v153
	v_max_f32_e32 v153, v229, v229
	v_mov_b32_e32 v155, 0
	v_cndmask_b32_e32 v152, v172, v152, vcc
	v_lshlrev_b32_e32 v152, 2, v152
	ds_bpermute_b32 v152, v152, v229
	v_mov_b32_e32 v229, 0
	s_waitcnt lgkmcnt(0)
	v_max_f32_e32 v152, v152, v152
	v_max_f32_e32 v152, v153, v152
	v_cmp_lt_f32_e32 vcc, s30, v152
	s_and_b64 s[18:19], s[78:79], vcc
	v_cmp_lt_f32_e32 vcc, s29, v152
	s_or_b64 s[78:79], vcc, s[18:19]
	s_and_saveexec_b64 s[18:19], s[78:79]
	v_add_f32_e32 v152, v203, v152
	v_cvt_pk_bf16_f32 v152, v152, 0
	v_lshlrev_b32_e32 v152, 16, v152
	v_sub_f32_e32 v229, v152, v203
	v_mov_b32_e32 v203, v152
	s_or_b64 exec, exec, s[18:19]
	v_exp_f32_e64 v152, -v229
	s_mov_b64 vcc, s[8:9]
	v_sub_f32_e32 v64, v64, v229
	v_sub_f32_e32 v65, v65, v229
	v_pk_mul_f32 v[46:47], v[46:47], v[152:153] op_sel_hi:[1,0]
	v_pk_mul_f32 v[44:45], v[44:45], v[152:153] op_sel_hi:[1,0]
	v_pk_mul_f32 v[42:43], v[42:43], v[152:153] op_sel_hi:[1,0]
	v_pk_mul_f32 v[40:41], v[40:41], v[152:153] op_sel_hi:[1,0]
	v_pk_mul_f32 v[38:39], v[38:39], v[152:153] op_sel_hi:[1,0]
	v_pk_mul_f32 v[36:37], v[36:37], v[152:153] op_sel_hi:[1,0]
	v_pk_mul_f32 v[34:35], v[34:35], v[152:153] op_sel_hi:[1,0]
	v_pk_mul_f32 v[32:33], v[32:33], v[152:153] op_sel_hi:[1,0]
	v_pk_mul_f32 v[30:31], v[30:31], v[152:153] op_sel_hi:[1,0]
	v_pk_mul_f32 v[28:29], v[28:29], v[152:153] op_sel_hi:[1,0]
	v_pk_mul_f32 v[26:27], v[26:27], v[152:153] op_sel_hi:[1,0]
	v_pk_mul_f32 v[24:25], v[24:25], v[152:153] op_sel_hi:[1,0]
	v_pk_mul_f32 v[22:23], v[22:23], v[152:153] op_sel_hi:[1,0]
	v_pk_mul_f32 v[20:21], v[20:21], v[152:153] op_sel_hi:[1,0]
	v_pk_mul_f32 v[18:19], v[18:19], v[152:153] op_sel_hi:[1,0]
	v_pk_mul_f32 v[16:17], v[16:17], v[152:153] op_sel_hi:[1,0]
	v_pk_mul_f32 v[14:15], v[14:15], v[152:153] op_sel_hi:[1,0]
	v_pk_mul_f32 v[12:13], v[12:13], v[152:153] op_sel_hi:[1,0]
	v_pk_mul_f32 v[10:11], v[10:11], v[152:153] op_sel_hi:[1,0]
	v_pk_mul_f32 v[8:9], v[8:9], v[152:153] op_sel_hi:[1,0]
	v_pk_mul_f32 v[6:7], v[6:7], v[152:153] op_sel_hi:[1,0]
	v_pk_mul_f32 v[4:5], v[4:5], v[152:153] op_sel_hi:[1,0]
	v_pk_mul_f32 v[2:3], v[2:3], v[152:153] op_sel_hi:[1,0]
	v_pk_mul_f32 v[0:1], v[0:1], v[152:153] op_sel_hi:[1,0]
	v_xor_b32_e32 v152, 0x80000000, v203
	v_sub_f32_e32 v66, v66, v229
	v_sub_f32_e32 v67, v67, v229
	v_sub_f32_e32 v68, v68, v229
	v_sub_f32_e32 v69, v69, v229
	v_sub_f32_e32 v70, v70, v229
	v_sub_f32_e32 v71, v71, v229
	v_sub_f32_e32 v72, v72, v229
	v_sub_f32_e32 v73, v73, v229
	v_sub_f32_e32 v74, v74, v229
	v_sub_f32_e32 v75, v75, v229
	v_sub_f32_e32 v76, v76, v229
	v_sub_f32_e32 v77, v77, v229
	v_sub_f32_e32 v78, v78, v229
	v_sub_f32_e32 v79, v79, v229
	v_sub_f32_e32 v48, v48, v229
	v_sub_f32_e32 v49, v49, v229
	v_sub_f32_e32 v50, v50, v229
	v_sub_f32_e32 v51, v51, v229
	v_sub_f32_e32 v52, v52, v229
	v_sub_f32_e32 v53, v53, v229
	v_sub_f32_e32 v54, v54, v229
	v_sub_f32_e32 v55, v55, v229
	v_sub_f32_e32 v56, v56, v229
	v_sub_f32_e32 v57, v57, v229
	v_sub_f32_e32 v58, v58, v229
	v_sub_f32_e32 v59, v59, v229
	v_sub_f32_e32 v60, v60, v229
	v_sub_f32_e32 v61, v61, v229
	v_sub_f32_e32 v62, v62, v229
	v_sub_f32_e32 v63, v63, v229
	v_cndmask_b32_sdwa v152, v113, v152, vcc dst_sel:DWORD dst_unused:UNUSED_PAD src0_sel:DWORD src1_sel:WORD_1
	v_mov_b32_e32 v154, 0
	v_mov_b32_e32 v153, 0
	s_branch .LBB0_451

.Lmo_437:
	s_mov_b32 s98, 0
	s_and_b32 s68, s73, 1
	s_add_i32 s74, s73, 1
	s_lshl_b32 s69, s68, 13
	s_cmp_lt_i32 s74, m0
	s_cbranch_scc1 .Lmla_fast_o
	v_cmp_ge_i32_e32 vcc, s74, v197
	s_and_saveexec_b64 s[18:19], vcc
	s_xor_b64 s[86:87], exec, s[18:19]
	s_cbranch_execz .Lmo_445
	v_cmp_lt_i32_e32 vcc, s73, v197
	s_and_saveexec_b64 s[78:79], vcc
	s_cbranch_execz .Lmo_444
	v_max_f32_e32 v48, v97, v97
	v_max_f32_e32 v49, v96, v96
	v_max_f32_e32 v48, v49, v48
	v_max3_f32 v48, v48, v98, v99
	v_max3_f32 v48, v48, v100, v101
	v_max3_f32 v48, v48, v102, v103
	v_max3_f32 v48, v48, v104, v105
	v_max3_f32 v48, v48, v106, v107
	v_max3_f32 v48, v48, v108, v109
	v_max3_f32 v48, v48, v110, v111
	v_max3_f32 v48, v48, v80, v81
	v_max3_f32 v48, v48, v82, v83
	v_max3_f32 v48, v48, v84, v85
	v_max3_f32 v48, v48, v86, v87
	v_max3_f32 v48, v48, v88, v89
	v_max3_f32 v48, v48, v90, v91
	v_max3_f32 v48, v48, v92, v93
	s_cmp_eq_u32 s73, 0
	v_max3_f32 v48, v48, v94, v95
	s_cselect_b64 s[18:19], -1, 0
	v_cmp_lt_f32_e32 vcc, s29, v48
	s_or_b64 vcc, s[18:19], vcc
	s_cbranch_vccz .Lmo_443
	v_and_b32_e32 v50, 64, v172
	v_xor_b32_e32 v49, 32, v172
	v_add_u32_e32 v50, 64, v50
	v_cmp_lt_i32_e32 vcc, v49, v50
	v_mov_b32_e32 v155, 0
	s_nop 0
	v_cndmask_b32_e32 v49, v172, v49, vcc
	v_lshlrev_b32_e32 v49, 2, v49
	ds_bpermute_b32 v49, v49, v48
	v_max_f32_e32 v48, v48, v48
	s_waitcnt lgkmcnt(0)
	v_max_f32_e32 v49, v49, v49
	v_max_f32_e32 v49, v48, v49
	v_cmp_lt_f32_e32 vcc, s30, v49
	s_and_b64 s[18:19], s[18:19], vcc
	v_cmp_lt_f32_e32 vcc, s29, v49
	s_or_b64 vcc, vcc, s[18:19]
	v_mov_b32_e32 v48, 0
	s_and_saveexec_b64 s[18:19], vcc
	v_add_f32_e32 v48, v203, v49
	v_cvt_pk_bf16_f32 v48, v48, 0
	v_lshlrev_b32_e32 v49, 16, v48
	v_sub_f32_e32 v48, v49, v203
	v_mov_b32_e32 v203, v49
	s_or_b64 exec, exec, s[18:19]
	v_exp_f32_e64 v50, -v48
	s_mov_b64 vcc, s[8:9]
	v_sub_f32_e32 v111, v111, v48
	v_sub_f32_e32 v110, v110, v48
	v_sub_f32_e32 v109, v109, v48
	v_sub_f32_e32 v108, v108, v48
	v_sub_f32_e32 v107, v107, v48
	v_sub_f32_e32 v106, v106, v48
	v_sub_f32_e32 v105, v105, v48
	v_sub_f32_e32 v104, v104, v48
	v_sub_f32_e32 v103, v103, v48
	v_sub_f32_e32 v102, v102, v48
	v_sub_f32_e32 v101, v101, v48
	v_sub_f32_e32 v100, v100, v48
	v_sub_f32_e32 v99, v99, v48
	v_sub_f32_e32 v98, v98, v48
	v_sub_f32_e32 v97, v97, v48
	v_sub_f32_e32 v96, v96, v48
	v_sub_f32_e32 v95, v95, v48
	v_sub_f32_e32 v94, v94, v48
	v_sub_f32_e32 v93, v93, v48
	v_sub_f32_e32 v92, v92, v48
	v_sub_f32_e32 v91, v91, v48
	v_sub_f32_e32 v90, v90, v48
	v_sub_f32_e32 v89, v89, v48
	v_sub_f32_e32 v88, v88, v48
	v_sub_f32_e32 v87, v87, v48
	v_sub_f32_e32 v86, v86, v48
	v_sub_f32_e32 v85, v85, v48
	v_sub_f32_e32 v84, v84, v48
	v_sub_f32_e32 v83, v83, v48
	v_sub_f32_e32 v82, v82, v48
	v_sub_f32_e32 v81, v81, v48
	v_sub_f32_e32 v80, v80, v48
	v_xor_b32_e32 v48, 0x80000000, v203
	v_pk_mul_f32 v[46:47], v[46:47], v[50:51] op_sel_hi:[1,0]
	v_pk_mul_f32 v[44:45], v[44:45], v[50:51] op_sel_hi:[1,0]
	v_pk_mul_f32 v[42:43], v[42:43], v[50:51] op_sel_hi:[1,0]
	v_pk_mul_f32 v[40:41], v[40:41], v[50:51] op_sel_hi:[1,0]
	v_pk_mul_f32 v[38:39], v[38:39], v[50:51] op_sel_hi:[1,0]
	v_pk_mul_f32 v[36:37], v[36:37], v[50:51] op_sel_hi:[1,0]
	v_pk_mul_f32 v[34:35], v[34:35], v[50:51] op_sel_hi:[1,0]
	v_pk_mul_f32 v[32:33], v[32:33], v[50:51] op_sel_hi:[1,0]
	v_pk_mul_f32 v[30:31], v[30:31], v[50:51] op_sel_hi:[1,0]
	v_pk_mul_f32 v[28:29], v[28:29], v[50:51] op_sel_hi:[1,0]
	v_pk_mul_f32 v[26:27], v[26:27], v[50:51] op_sel_hi:[1,0]
	v_pk_mul_f32 v[24:25], v[24:25], v[50:51] op_sel_hi:[1,0]
	v_pk_mul_f32 v[22:23], v[22:23], v[50:51] op_sel_hi:[1,0]
	v_pk_mul_f32 v[20:21], v[20:21], v[50:51] op_sel_hi:[1,0]
	v_pk_mul_f32 v[18:19], v[18:19], v[50:51] op_sel_hi:[1,0]
	v_pk_mul_f32 v[16:17], v[16:17], v[50:51] op_sel_hi:[1,0]
	v_pk_mul_f32 v[14:15], v[14:15], v[50:51] op_sel_hi:[1,0]
	v_pk_mul_f32 v[12:13], v[12:13], v[50:51] op_sel_hi:[1,0]
	v_pk_mul_f32 v[10:11], v[10:11], v[50:51] op_sel_hi:[1,0]
	v_pk_mul_f32 v[8:9], v[8:9], v[50:51] op_sel_hi:[1,0]
	v_pk_mul_f32 v[6:7], v[6:7], v[50:51] op_sel_hi:[1,0]
	v_pk_mul_f32 v[4:5], v[4:5], v[50:51] op_sel_hi:[1,0]
	v_pk_mul_f32 v[2:3], v[2:3], v[50:51] op_sel_hi:[1,0]
	v_pk_mul_f32 v[0:1], v[0:1], v[50:51] op_sel_hi:[1,0]
	v_cndmask_b32_sdwa v152, v113, v48, vcc dst_sel:DWORD dst_unused:UNUSED_PAD src0_sel:DWORD src1_sel:WORD_1
	v_mov_b32_e32 v154, 0
	v_mov_b32_e32 v153, 0

.Lmla_fast_o:
	ds_read_b128 v[174:177], v186 offset:0
	ds_read_b128 v[204:207], v186 offset:8192
	v_mfma_f32_32x32x16_bf16 v[48:63], v[112:115], v[152:155], 0
	ds_read_b128 v[208:211], v184 offset:0
	ds_read_b128 v[212:215], v184 offset:8192
	ds_read_b128 v[216:219], v183 offset:0
	ds_read_b128 v[220:223], v183 offset:8192
	ds_read_b128 v[230:233], v191 offset:0
	ds_read_b128 v[234:237], v191 offset:8192
	ds_read_b128 v[238:241], v190 offset:0
	ds_read_b128 v[242:245], v190 offset:8192
	ds_read_b128 v[246:249], v187 offset:0
	ds_read_b128 v[250:253], v187 offset:8192
	s_cmp_eq_u32 s73, 0
	s_cselect_b64 s[78:79], -1, 0
	v_max_f32_e32 v224, v97, v97
	v_max_f32_e32 v225, v96, v96
	v_max_f32_e32 v224, v225, v224
	v_max3_f32 v224, v224, v98, v99
	v_max3_f32 v224, v224, v100, v101
	s_waitcnt lgkmcnt(11)
	v_mfma_f32_32x32x16_bf16 v[64:79], v[174:177], v[116:119], v[48:63]
	v_max3_f32 v224, v224, v102, v103
	v_max3_f32 v224, v224, v104, v105
	v_max3_f32 v224, v224, v106, v107
	v_max3_f32 v224, v224, v108, v109
	v_max3_f32 v224, v224, v110, v111
	v_max3_f32 v224, v224, v80, v81
	s_waitcnt lgkmcnt(10)
	v_mfma_f32_32x32x16_bf16 v[48:63], v[204:207], v[116:119], v[48:63]
	ds_read_b128 v[174:177], v199 offset:40960
	v_max3_f32 v224, v224, v82, v83
	v_max3_f32 v224, v224, v84, v85
	v_max3_f32 v224, v224, v86, v87
	v_max3_f32 v224, v224, v88, v89
	v_max3_f32 v224, v224, v90, v91
	v_max3_f32 v224, v224, v92, v93
	v_max3_f32 v229, v224, v94, v95
	v_cmp_lt_f32_e32 vcc, s29, v229
	s_or_b64 vcc, s[78:79], vcc
	s_waitcnt lgkmcnt(10)
	v_mfma_f32_32x32x16_bf16 v[64:79], v[208:211], v[120:123], v[64:79]
	ds_read_b128 v[204:207], v199 offset:45056
	s_cbranch_vccz .Lmo_450
	v_and_b32_e32 v153, 64, v172
	v_xor_b32_e32 v152, 32, v172
	v_add_u32_e32 v153, 64, v153
	v_cmp_lt_i32_e32 vcc, v152, v153
	v_max_f32_e32 v153, v229, v229
	v_mov_b32_e32 v155, 0
	v_cndmask_b32_e32 v152, v172, v152, vcc
	v_lshlrev_b32_e32 v152, 2, v152
	ds_bpermute_b32 v152, v152, v229
	v_mov_b32_e32 v229, 0
	s_waitcnt lgkmcnt(0)
	v_max_f32_e32 v152, v152, v152
	v_max_f32_e32 v152, v153, v152
	v_cmp_lt_f32_e32 vcc, s30, v152
	s_and_b64 s[18:19], s[78:79], vcc
	v_cmp_lt_f32_e32 vcc, s29, v152
	s_or_b64 s[78:79], vcc, s[18:19]
	s_and_saveexec_b64 s[18:19], s[78:79]
	v_add_f32_e32 v152, v203, v152
	v_cvt_pk_bf16_f32 v152, v152, 0
	v_lshlrev_b32_e32 v152, 16, v152
	v_sub_f32_e32 v229, v152, v203
	v_mov_b32_e32 v203, v152
	s_or_b64 exec, exec, s[18:19]
	v_exp_f32_e64 v152, -v229
	s_mov_b64 vcc, s[8:9]
	v_sub_f32_e32 v96, v96, v229
	v_sub_f32_e32 v97, v97, v229
	v_pk_mul_f32 v[46:47], v[46:47], v[152:153] op_sel_hi:[1,0]
	v_pk_mul_f32 v[44:45], v[44:45], v[152:153] op_sel_hi:[1,0]
	v_pk_mul_f32 v[42:43], v[42:43], v[152:153] op_sel_hi:[1,0]
	v_pk_mul_f32 v[40:41], v[40:41], v[152:153] op_sel_hi:[1,0]
	v_pk_mul_f32 v[38:39], v[38:39], v[152:153] op_sel_hi:[1,0]
	v_pk_mul_f32 v[36:37], v[36:37], v[152:153] op_sel_hi:[1,0]
	v_pk_mul_f32 v[34:35], v[34:35], v[152:153] op_sel_hi:[1,0]
	v_pk_mul_f32 v[32:33], v[32:33], v[152:153] op_sel_hi:[1,0]
	v_pk_mul_f32 v[30:31], v[30:31], v[152:153] op_sel_hi:[1,0]
	v_pk_mul_f32 v[28:29], v[28:29], v[152:153] op_sel_hi:[1,0]
	v_pk_mul_f32 v[26:27], v[26:27], v[152:153] op_sel_hi:[1,0]
	v_pk_mul_f32 v[24:25], v[24:25], v[152:153] op_sel_hi:[1,0]
	v_pk_mul_f32 v[22:23], v[22:23], v[152:153] op_sel_hi:[1,0]
	v_pk_mul_f32 v[20:21], v[20:21], v[152:153] op_sel_hi:[1,0]
	v_pk_mul_f32 v[18:19], v[18:19], v[152:153] op_sel_hi:[1,0]
	v_pk_mul_f32 v[16:17], v[16:17], v[152:153] op_sel_hi:[1,0]
	v_pk_mul_f32 v[14:15], v[14:15], v[152:153] op_sel_hi:[1,0]
	v_pk_mul_f32 v[12:13], v[12:13], v[152:153] op_sel_hi:[1,0]
	v_pk_mul_f32 v[10:11], v[10:11], v[152:153] op_sel_hi:[1,0]
	v_pk_mul_f32 v[8:9], v[8:9], v[152:153] op_sel_hi:[1,0]
	v_pk_mul_f32 v[6:7], v[6:7], v[152:153] op_sel_hi:[1,0]
	v_pk_mul_f32 v[4:5], v[4:5], v[152:153] op_sel_hi:[1,0]
	v_pk_mul_f32 v[2:3], v[2:3], v[152:153] op_sel_hi:[1,0]
	v_pk_mul_f32 v[0:1], v[0:1], v[152:153] op_sel_hi:[1,0]
	v_xor_b32_e32 v152, 0x80000000, v203
	v_sub_f32_e32 v98, v98, v229
	v_sub_f32_e32 v99, v99, v229
	v_sub_f32_e32 v100, v100, v229
	v_sub_f32_e32 v101, v101, v229
	v_sub_f32_e32 v102, v102, v229
	v_sub_f32_e32 v103, v103, v229
	v_sub_f32_e32 v104, v104, v229
	v_sub_f32_e32 v105, v105, v229
	v_sub_f32_e32 v106, v106, v229
	v_sub_f32_e32 v107, v107, v229
	v_sub_f32_e32 v108, v108, v229
	v_sub_f32_e32 v109, v109, v229
	v_sub_f32_e32 v110, v110, v229
	v_sub_f32_e32 v111, v111, v229
	v_sub_f32_e32 v80, v80, v229
	v_sub_f32_e32 v81, v81, v229
	v_sub_f32_e32 v82, v82, v229
	v_sub_f32_e32 v83, v83, v229
	v_sub_f32_e32 v84, v84, v229
	v_sub_f32_e32 v85, v85, v229
	v_sub_f32_e32 v86, v86, v229
	v_sub_f32_e32 v87, v87, v229
	v_sub_f32_e32 v88, v88, v229
	v_sub_f32_e32 v89, v89, v229
	v_sub_f32_e32 v90, v90, v229
	v_sub_f32_e32 v91, v91, v229
	v_sub_f32_e32 v92, v92, v229
	v_sub_f32_e32 v93, v93, v229
	v_sub_f32_e32 v94, v94, v229
	v_sub_f32_e32 v95, v95, v229
	v_cndmask_b32_sdwa v152, v113, v152, vcc dst_sel:DWORD dst_unused:UNUSED_PAD src0_sel:DWORD src1_sel:WORD_1
	v_mov_b32_e32 v154, 0
	v_mov_b32_e32 v153, 0
	s_branch .Lmo_451
